# seam after the prep phase now uses the same XCD-hierarchical grid barrier as every other seam (cooperative-groups grid.sync path no longer taken)
# speedup vs baseline: 1.0026x; 1.0026x over previous
; #define LAS __attribute__((address_space(3)))
; __device__ __forceinline__ unsigned xb_xcc_id() { return (unsigned)__builtin_amdgcn_s_getreg((3 << 11) | 20) & 0xFu; }
; __device__ __forceinline__ void xcd_barrier(const XcdBarrier& b) {
;     asm volatile("s_waitcnt vmcnt(0)" ::: "memory");
;     __syncthreads();
;     if (threadIdx.x == 0) {
;         unsigned* bar = b.bar;
;         __builtin_amdgcn_s_waitcnt(0);
;         unsigned nloc = b.st[0], nx = b.st[1];
;         if (nloc == 0u) { xcd_barrier_complete(bar, b.x, nloc, nx); b.st[0] = nloc; b.st[1] = nx; }
; __global__ void __launch_bounds__(NTHR) hyena_swa_fwd(Params P) {
;     ...
;         if (ph + 1 < N_PHASES) {
;             if (ph == 0) {
;                 asm volatile("s_waitcnt vmcnt(0) lgkmcnt(0)" ::: "memory");
;                 __syncthreads();
;                 if (wave == 0) { __builtin_amdgcn_fence(__ATOMIC_RELEASE, "agent"); asm volatile("s_waitcnt vmcnt(0)" ::: "memory"); }
;                 grid.sync();
;                 if (wave == 0) { __builtin_amdgcn_fence(__ATOMIC_ACQUIRE, "agent"); asm volatile("s_waitcnt vmcnt(0)" ::: "memory"); }
;                 __syncthreads();
;             } else if (ph != 1 && ph != 8 && ph != 17) {
;                 XcdBarrier xb; xb.bar = (unsigned*)(Q.ws + WS_BAR); xb.x = xb_xcc_id(); xb.st = (volatile LAS unsigned*)(lds + MISC_OFF + 12288);
;                 xcd_barrier(xb);
;             }
.LBB0_848:
	s_cmp_lg_u32 s55, 0
	s_mov_b64 s[2:3], -1
	s_cselect_b64 s[0:1], -1, 0
	s_andn2_b64 vcc, exec, s[0:1]
	s_mov_b64 s[0:1], 0
.LBB0_849:
	s_cmp_lg_u32 s55, 8
	s_cselect_b64 s[0:1], -1, 0
	s_and_b32 s2, s55, 15
	s_cmp_lg_u32 s2, 1
	s_cselect_b64 s[2:3], -1, 0
	s_and_b64 s[0:1], s[0:1], s[2:3]
	s_mov_b64 s[2:3], 0
	s_and_b64 vcc, exec, s[0:1]
	s_mov_b64 s[0:1], 0
	s_cbranch_vccz .LBB0_895
	s_getreg_b32 s0, hwreg(HW_REG_XCC_ID, 0, 4)
	s_waitcnt vmcnt(0)
	s_waitcnt vmcnt(0) lgkmcnt(0)
	s_barrier
	s_mov_b64 s[16:17], exec
	v_readlane_b32 s4, v253, 5
	v_readlane_b32 s5, v253, 6
	s_and_b64 s[4:5], s[16:17], s[4:5]
	s_mov_b64 exec, s[4:5]
	s_cbranch_execz .LBB0_894
	v_readlane_b32 s1, v254, 33
	s_waitcnt vmcnt(0) expcnt(0) lgkmcnt(0)
	s_and_b32 s42, s0, 15
	v_mov_b32_e32 v0, s1
	ds_read_b32 v2, v0
	v_readlane_b32 s1, v254, 34
	s_waitcnt lgkmcnt(0)
	v_cmp_ne_u32_e32 vcc, 0, v2
	v_mov_b32_e32 v0, s1
	ds_read_b32 v0, v0
	s_cbranch_vccnz .LBB0_865
	s_add_u32 s0, s66, 0x3f800200
	s_addc_u32 s1, s67, 0
	s_add_u32 s4, s66, 0x3f800400
	s_addc_u32 s5, s67, 0
	s_add_u32 s6, s66, 0x3f800500
	s_addc_u32 s7, s67, 0
	s_add_u32 s8, s66, 0x3f800600
	s_addc_u32 s9, s67, 0
	s_add_u32 s10, s66, 0x3f800700
	s_addc_u32 s11, s67, 0
	s_add_u32 s12, s66, 0x3f800800
	s_addc_u32 s13, s67, 0
	s_add_u32 s14, s66, 0x3f800900
	s_addc_u32 s15, s67, 0
	s_add_u32 s18, s66, 0x3f800a00
	s_addc_u32 s19, s67, 0
	s_add_u32 s20, s66, 0x3f800b00
	s_addc_u32 s21, s67, 0
	s_add_u32 s22, s66, 0x3f800c00
	s_addc_u32 s23, s67, 0
	s_add_u32 s24, s66, 0x3f800d00
	s_addc_u32 s25, s67, 0
	s_add_u32 s26, s66, 0x3f800e00
	s_addc_u32 s27, s67, 0
	s_add_u32 s28, s66, 0x3f800f00
	s_addc_u32 s29, s67, 0
	s_add_u32 s30, s66, 0x3f801000
	s_addc_u32 s31, s67, 0
	s_add_u32 s34, s66, 0x3f801100
	s_addc_u32 s35, s67, 0
	s_add_u32 s36, s66, 0x3f801200
	s_addc_u32 s37, s67, 0
	s_add_u32 s66, s66, 0x3f801300
	s_addc_u32 s67, s67, 0
	s_mov_b32 s55, 1
	s_mov_b64 s[68:69], 0
	s_branch .LBB0_855
